# phase 6 epilogue: nt stores only for the gate tiles; q_c / kv_r tiles (read by the next phase) keep the default policy
# speedup vs baseline: 1.0045x; 1.0045x over previous
.LBB0_623:
	v_cvt_pk_bf16_f32 v124, v124, v125
	v_cvt_pk_bf16_f32 v125, v126, v127
	v_cvt_pk_bf16_f32 v126, v120, v121
	v_cvt_pk_bf16_f32 v127, v122, v123
	s_and_b64 vcc, exec, s[6:7]
	s_cbranch_vccz .Lp6nt_0
	global_store_dwordx4 v[146:147], v[124:127], off
	s_branch .LBB0_625
.Lp6nt_0:
	global_store_dwordx4 v[146:147], v[124:127], off nt
	s_mov_b32 s100, 0xbfb8aa3b
	v_pk_mul_f32 v[120:121], v[116:117], s[100:101] op_sel_hi:[1,0]
	v_pk_mul_f32 v[122:123], v[118:119], s[100:101] op_sel_hi:[1,0]
	v_pk_mul_f32 v[124:125], v[112:113], s[100:101] op_sel_hi:[1,0]
	v_pk_mul_f32 v[126:127], v[114:115], s[100:101] op_sel_hi:[1,0]
	v_exp_f32_e32 v120, v120
	v_exp_f32_e32 v121, v121
	v_exp_f32_e32 v122, v122
	v_exp_f32_e32 v123, v123
	v_exp_f32_e32 v124, v124
	v_exp_f32_e32 v125, v125
	v_exp_f32_e32 v126, v126
	v_exp_f32_e32 v127, v127
	v_pk_add_f32 v[120:121], v[120:121], 1.0 op_sel_hi:[1,0]
	v_pk_add_f32 v[122:123], v[122:123], 1.0 op_sel_hi:[1,0]
	v_pk_add_f32 v[124:125], v[124:125], 1.0 op_sel_hi:[1,0]
	v_pk_add_f32 v[126:127], v[126:127], 1.0 op_sel_hi:[1,0]
	v_rcp_f32_e32 v120, v120
	v_rcp_f32_e32 v121, v121
	v_rcp_f32_e32 v122, v122
	v_rcp_f32_e32 v123, v123
	v_rcp_f32_e32 v124, v124
	v_rcp_f32_e32 v126, v126
	v_rcp_f32_e32 v127, v127
	v_rcp_f32_e32 v125, v125
	v_pk_mul_f32 v[118:119], v[118:119], v[122:123]
	v_pk_mul_f32 v[116:117], v[116:117], v[120:121]
	v_pk_mul_f32 v[114:115], v[114:115], v[126:127]
	v_pk_mul_f32 v[112:113], v[112:113], v[124:125]
.LBB0_625:
	s_lshl_b32 s58, s58, 1
	s_mov_b32 s59, s1
	v_cvt_pk_bf16_f32 v116, v116, v117
	v_cvt_pk_bf16_f32 v117, v118, v119
	v_cvt_pk_bf16_f32 v118, v112, v113
	v_cvt_pk_bf16_f32 v119, v114, v115
	v_lshl_add_u64 v[112:113], v[146:147], 0, s[58:59]
	s_and_b64 vcc, exec, s[6:7]
	s_cbranch_vccz .Lp6nt_1
	global_store_dwordx4 v[112:113], v[116:119], off
	s_branch .LBB0_627
.Lp6nt_1:
	global_store_dwordx4 v[112:113], v[116:119], off nt
	s_mov_b32 s100, 0xbfb8aa3b
	v_pk_mul_f32 v[112:113], v[108:109], s[100:101] op_sel_hi:[1,0]
	v_pk_mul_f32 v[114:115], v[110:111], s[100:101] op_sel_hi:[1,0]
	v_pk_mul_f32 v[116:117], v[104:105], s[100:101] op_sel_hi:[1,0]
	v_pk_mul_f32 v[118:119], v[106:107], s[100:101] op_sel_hi:[1,0]
	v_exp_f32_e32 v112, v112
	v_exp_f32_e32 v113, v113
	v_exp_f32_e32 v114, v114
	v_exp_f32_e32 v115, v115
	v_exp_f32_e32 v116, v116
	v_exp_f32_e32 v117, v117
	v_exp_f32_e32 v118, v118
	v_exp_f32_e32 v119, v119
	v_pk_add_f32 v[112:113], v[112:113], 1.0 op_sel_hi:[1,0]
	v_pk_add_f32 v[114:115], v[114:115], 1.0 op_sel_hi:[1,0]
	v_pk_add_f32 v[116:117], v[116:117], 1.0 op_sel_hi:[1,0]
	v_pk_add_f32 v[118:119], v[118:119], 1.0 op_sel_hi:[1,0]
	v_rcp_f32_e32 v112, v112
	v_rcp_f32_e32 v113, v113
	v_rcp_f32_e32 v114, v114
	v_rcp_f32_e32 v115, v115
	v_rcp_f32_e32 v116, v116
	v_rcp_f32_e32 v118, v118
	v_rcp_f32_e32 v119, v119
	v_rcp_f32_e32 v117, v117
	v_pk_mul_f32 v[110:111], v[110:111], v[114:115]
	v_pk_mul_f32 v[108:109], v[108:109], v[112:113]
	v_pk_mul_f32 v[106:107], v[106:107], v[118:119]
	v_pk_mul_f32 v[104:105], v[104:105], v[116:117]
.LBB0_627:
	s_lshl_b32 s0, s60, 5
	v_lshl_add_u64 v[112:113], v[146:147], 0, s[0:1]
	v_cvt_pk_bf16_f32 v108, v108, v109
	v_cvt_pk_bf16_f32 v109, v110, v111
	v_cvt_pk_bf16_f32 v110, v104, v105
	v_cvt_pk_bf16_f32 v111, v106, v107
	s_and_b64 vcc, exec, s[6:7]
	s_cbranch_vccz .Lp6nt_2
	global_store_dwordx4 v[112:113], v[108:111], off
	s_branch .LBB0_629
.Lp6nt_2:
	global_store_dwordx4 v[112:113], v[108:111], off nt
	s_mov_b32 s100, 0xbfb8aa3b
	v_pk_mul_f32 v[104:105], v[100:101], s[100:101] op_sel_hi:[1,0]
	v_pk_mul_f32 v[106:107], v[102:103], s[100:101] op_sel_hi:[1,0]
	v_pk_mul_f32 v[108:109], v[96:97], s[100:101] op_sel_hi:[1,0]
	v_pk_mul_f32 v[110:111], v[98:99], s[100:101] op_sel_hi:[1,0]
	v_exp_f32_e32 v104, v104
	v_exp_f32_e32 v105, v105
	v_exp_f32_e32 v106, v106
	v_exp_f32_e32 v107, v107
	v_exp_f32_e32 v108, v108
	v_exp_f32_e32 v109, v109
	v_exp_f32_e32 v110, v110
	v_exp_f32_e32 v111, v111
	v_pk_add_f32 v[104:105], v[104:105], 1.0 op_sel_hi:[1,0]
	v_pk_add_f32 v[106:107], v[106:107], 1.0 op_sel_hi:[1,0]
	v_pk_add_f32 v[108:109], v[108:109], 1.0 op_sel_hi:[1,0]
	v_pk_add_f32 v[110:111], v[110:111], 1.0 op_sel_hi:[1,0]
	v_rcp_f32_e32 v104, v104
	v_rcp_f32_e32 v105, v105
	v_rcp_f32_e32 v106, v106
	v_rcp_f32_e32 v107, v107
	v_rcp_f32_e32 v108, v108
	v_rcp_f32_e32 v110, v110
	v_rcp_f32_e32 v111, v111
	v_rcp_f32_e32 v109, v109
	v_pk_mul_f32 v[102:103], v[102:103], v[106:107]
	v_pk_mul_f32 v[100:101], v[100:101], v[104:105]
	v_pk_mul_f32 v[98:99], v[98:99], v[110:111]
	v_pk_mul_f32 v[96:97], v[96:97], v[108:109]
.LBB0_629:
	s_mov_b32 s59, s1
	v_cvt_pk_bf16_f32 v100, v100, v101
	v_cvt_pk_bf16_f32 v101, v102, v103
	v_cvt_pk_bf16_f32 v102, v96, v97
	v_cvt_pk_bf16_f32 v103, v98, v99
	v_lshl_add_u64 v[96:97], v[112:113], 0, s[58:59]
	s_and_b64 vcc, exec, s[6:7]
	s_cbranch_vccz .Lp6nt_3
	global_store_dwordx4 v[96:97], v[100:103], off
	s_branch .LBB0_631
.Lp6nt_3:
	global_store_dwordx4 v[96:97], v[100:103], off nt
	s_mov_b32 s100, 0xbfb8aa3b
	v_pk_mul_f32 v[96:97], v[92:93], s[100:101] op_sel_hi:[1,0]
	v_pk_mul_f32 v[98:99], v[94:95], s[100:101] op_sel_hi:[1,0]
	v_pk_mul_f32 v[100:101], v[88:89], s[100:101] op_sel_hi:[1,0]
	v_pk_mul_f32 v[102:103], v[90:91], s[100:101] op_sel_hi:[1,0]
	v_exp_f32_e32 v96, v96
	v_exp_f32_e32 v97, v97
	v_exp_f32_e32 v98, v98
	v_exp_f32_e32 v99, v99
	v_exp_f32_e32 v100, v100
	v_exp_f32_e32 v101, v101
	v_exp_f32_e32 v102, v102
	v_exp_f32_e32 v103, v103
	v_pk_add_f32 v[96:97], v[96:97], 1.0 op_sel_hi:[1,0]
	v_pk_add_f32 v[98:99], v[98:99], 1.0 op_sel_hi:[1,0]
	v_pk_add_f32 v[100:101], v[100:101], 1.0 op_sel_hi:[1,0]
	v_pk_add_f32 v[102:103], v[102:103], 1.0 op_sel_hi:[1,0]
	v_rcp_f32_e32 v96, v96
	v_rcp_f32_e32 v97, v97
	v_rcp_f32_e32 v98, v98
	v_rcp_f32_e32 v99, v99
	v_rcp_f32_e32 v100, v100
	v_rcp_f32_e32 v102, v102
	v_rcp_f32_e32 v103, v103
	v_rcp_f32_e32 v101, v101
	v_pk_mul_f32 v[94:95], v[94:95], v[98:99]
	v_pk_mul_f32 v[92:93], v[92:93], v[96:97]
	v_pk_mul_f32 v[90:91], v[90:91], v[102:103]
	v_pk_mul_f32 v[88:89], v[88:89], v[100:101]
.LBB0_631:
	v_lshl_add_u64 v[96:97], v[112:113], 0, s[0:1]
	v_cvt_pk_bf16_f32 v92, v92, v93
	v_cvt_pk_bf16_f32 v93, v94, v95
	v_cvt_pk_bf16_f32 v94, v88, v89
	v_cvt_pk_bf16_f32 v95, v90, v91
	s_and_b64 vcc, exec, s[6:7]
	s_cbranch_vccz .Lp6nt_4
	global_store_dwordx4 v[96:97], v[92:95], off
	s_branch .LBB0_633
.Lp6nt_4:
	global_store_dwordx4 v[96:97], v[92:95], off nt
	s_mov_b32 s100, 0xbfb8aa3b
	v_pk_mul_f32 v[88:89], v[84:85], s[100:101] op_sel_hi:[1,0]
	v_pk_mul_f32 v[90:91], v[86:87], s[100:101] op_sel_hi:[1,0]
	v_pk_mul_f32 v[92:93], v[80:81], s[100:101] op_sel_hi:[1,0]
	v_pk_mul_f32 v[94:95], v[82:83], s[100:101] op_sel_hi:[1,0]
	v_exp_f32_e32 v88, v88
	v_exp_f32_e32 v89, v89
	v_exp_f32_e32 v90, v90
	v_exp_f32_e32 v91, v91
	v_exp_f32_e32 v92, v92
	v_exp_f32_e32 v93, v93
	v_exp_f32_e32 v94, v94
	v_exp_f32_e32 v95, v95
	v_pk_add_f32 v[88:89], v[88:89], 1.0 op_sel_hi:[1,0]
	v_pk_add_f32 v[90:91], v[90:91], 1.0 op_sel_hi:[1,0]
	v_pk_add_f32 v[92:93], v[92:93], 1.0 op_sel_hi:[1,0]
	v_pk_add_f32 v[94:95], v[94:95], 1.0 op_sel_hi:[1,0]
	v_rcp_f32_e32 v88, v88
	v_rcp_f32_e32 v89, v89
	v_rcp_f32_e32 v90, v90
	v_rcp_f32_e32 v91, v91
	v_rcp_f32_e32 v92, v92
	v_rcp_f32_e32 v94, v94
	v_rcp_f32_e32 v95, v95
	v_rcp_f32_e32 v93, v93
	v_pk_mul_f32 v[86:87], v[86:87], v[90:91]
	v_pk_mul_f32 v[84:85], v[84:85], v[88:89]
	v_pk_mul_f32 v[82:83], v[82:83], v[94:95]
	v_pk_mul_f32 v[80:81], v[80:81], v[92:93]
.LBB0_633:
	s_mov_b32 s59, s1
	v_cvt_pk_bf16_f32 v84, v84, v85
	v_cvt_pk_bf16_f32 v85, v86, v87
	v_cvt_pk_bf16_f32 v86, v80, v81
	v_cvt_pk_bf16_f32 v87, v82, v83
	v_lshl_add_u64 v[80:81], v[96:97], 0, s[58:59]
	s_and_b64 vcc, exec, s[6:7]
	s_cbranch_vccz .Lp6nt_5
	global_store_dwordx4 v[80:81], v[84:87], off
	s_branch .LBB0_635
.Lp6nt_5:
	global_store_dwordx4 v[80:81], v[84:87], off nt
	s_mov_b32 s100, 0xbfb8aa3b
	v_pk_mul_f32 v[80:81], v[76:77], s[100:101] op_sel_hi:[1,0]
	v_pk_mul_f32 v[82:83], v[78:79], s[100:101] op_sel_hi:[1,0]
	v_pk_mul_f32 v[84:85], v[72:73], s[100:101] op_sel_hi:[1,0]
	v_pk_mul_f32 v[86:87], v[74:75], s[100:101] op_sel_hi:[1,0]
	v_exp_f32_e32 v80, v80
	v_exp_f32_e32 v81, v81
	v_exp_f32_e32 v82, v82
	v_exp_f32_e32 v83, v83
	v_exp_f32_e32 v84, v84
	v_exp_f32_e32 v85, v85
	v_exp_f32_e32 v86, v86
	v_exp_f32_e32 v87, v87
	v_pk_add_f32 v[80:81], v[80:81], 1.0 op_sel_hi:[1,0]
	v_pk_add_f32 v[82:83], v[82:83], 1.0 op_sel_hi:[1,0]
	v_pk_add_f32 v[84:85], v[84:85], 1.0 op_sel_hi:[1,0]
	v_pk_add_f32 v[86:87], v[86:87], 1.0 op_sel_hi:[1,0]
	v_rcp_f32_e32 v80, v80
	v_rcp_f32_e32 v81, v81
	v_rcp_f32_e32 v82, v82
	v_rcp_f32_e32 v83, v83
	v_rcp_f32_e32 v84, v84
	v_rcp_f32_e32 v86, v86
	v_rcp_f32_e32 v87, v87
	v_rcp_f32_e32 v85, v85
	v_pk_mul_f32 v[78:79], v[78:79], v[82:83]
	v_pk_mul_f32 v[76:77], v[76:77], v[80:81]
	v_pk_mul_f32 v[74:75], v[74:75], v[86:87]
	v_pk_mul_f32 v[72:73], v[72:73], v[84:85]
.LBB0_635:
	v_lshl_add_u64 v[80:81], v[96:97], 0, s[0:1]
	v_cvt_pk_bf16_f32 v76, v76, v77
	v_cvt_pk_bf16_f32 v77, v78, v79
	v_cvt_pk_bf16_f32 v78, v72, v73
	v_cvt_pk_bf16_f32 v79, v74, v75
	s_and_b64 vcc, exec, s[6:7]
	s_cbranch_vccz .Lp6nt_6
	global_store_dwordx4 v[80:81], v[76:79], off
	s_branch .LBB0_637
.Lp6nt_6:
	global_store_dwordx4 v[80:81], v[76:79], off nt
	s_mov_b32 s100, 0xbfb8aa3b
	v_pk_mul_f32 v[72:73], v[68:69], s[100:101] op_sel_hi:[1,0]
	v_pk_mul_f32 v[74:75], v[70:71], s[100:101] op_sel_hi:[1,0]
	v_pk_mul_f32 v[76:77], v[64:65], s[100:101] op_sel_hi:[1,0]
	v_pk_mul_f32 v[78:79], v[66:67], s[100:101] op_sel_hi:[1,0]
	v_exp_f32_e32 v72, v72
	v_exp_f32_e32 v73, v73
	v_exp_f32_e32 v74, v74
	v_exp_f32_e32 v75, v75
	v_exp_f32_e32 v76, v76
	v_exp_f32_e32 v77, v77
	v_exp_f32_e32 v78, v78
	v_exp_f32_e32 v79, v79
	v_pk_add_f32 v[72:73], v[72:73], 1.0 op_sel_hi:[1,0]
	v_pk_add_f32 v[74:75], v[74:75], 1.0 op_sel_hi:[1,0]
	v_pk_add_f32 v[76:77], v[76:77], 1.0 op_sel_hi:[1,0]
	v_pk_add_f32 v[78:79], v[78:79], 1.0 op_sel_hi:[1,0]
	v_rcp_f32_e32 v72, v72
	v_rcp_f32_e32 v73, v73
	v_rcp_f32_e32 v74, v74
	v_rcp_f32_e32 v75, v75
	v_rcp_f32_e32 v76, v76
	v_rcp_f32_e32 v78, v78
	v_rcp_f32_e32 v79, v79
	v_rcp_f32_e32 v77, v77
	v_pk_mul_f32 v[70:71], v[70:71], v[74:75]
	v_pk_mul_f32 v[68:69], v[68:69], v[72:73]
	v_pk_mul_f32 v[66:67], v[66:67], v[78:79]
	v_pk_mul_f32 v[64:65], v[64:65], v[76:77]
.LBB0_637:
	s_mov_b32 s59, s1
	v_cvt_pk_bf16_f32 v68, v68, v69
	v_cvt_pk_bf16_f32 v69, v70, v71
	v_cvt_pk_bf16_f32 v70, v64, v65
	v_cvt_pk_bf16_f32 v71, v66, v67
	v_lshl_add_u64 v[64:65], v[80:81], 0, s[58:59]
	s_and_b64 vcc, exec, s[6:7]
	s_cbranch_vccz .Lp6nt_7
	global_store_dwordx4 v[64:65], v[68:71], off
	s_branch .LBB0_639
.Lp6nt_7:
	global_store_dwordx4 v[64:65], v[68:71], off nt
	s_mov_b32 s100, 0xbfb8aa3b
	v_pk_mul_f32 v[64:65], v[60:61], s[100:101] op_sel_hi:[1,0]
	v_pk_mul_f32 v[66:67], v[62:63], s[100:101] op_sel_hi:[1,0]
	v_pk_mul_f32 v[68:69], v[56:57], s[100:101] op_sel_hi:[1,0]
	v_pk_mul_f32 v[70:71], v[58:59], s[100:101] op_sel_hi:[1,0]
	v_exp_f32_e32 v64, v64
	v_exp_f32_e32 v65, v65
	v_exp_f32_e32 v66, v66
	v_exp_f32_e32 v67, v67
	v_exp_f32_e32 v68, v68
	v_exp_f32_e32 v69, v69
	v_exp_f32_e32 v70, v70
	v_exp_f32_e32 v71, v71
	v_pk_add_f32 v[64:65], v[64:65], 1.0 op_sel_hi:[1,0]
	v_pk_add_f32 v[66:67], v[66:67], 1.0 op_sel_hi:[1,0]
	v_pk_add_f32 v[68:69], v[68:69], 1.0 op_sel_hi:[1,0]
	v_pk_add_f32 v[70:71], v[70:71], 1.0 op_sel_hi:[1,0]
	v_rcp_f32_e32 v64, v64
	v_rcp_f32_e32 v65, v65
	v_rcp_f32_e32 v66, v66
	v_rcp_f32_e32 v67, v67
	v_rcp_f32_e32 v68, v68
	v_rcp_f32_e32 v70, v70
	v_rcp_f32_e32 v71, v71
	v_rcp_f32_e32 v69, v69
	v_pk_mul_f32 v[62:63], v[62:63], v[66:67]
	v_pk_mul_f32 v[60:61], v[60:61], v[64:65]
	v_pk_mul_f32 v[58:59], v[58:59], v[70:71]
	v_pk_mul_f32 v[56:57], v[56:57], v[68:69]
.LBB0_639:
	s_mulk_i32 s60, 0xa0
	s_mov_b32 s61, s1
	v_lshl_add_u64 v[64:65], v[80:81], 0, s[60:61]
	v_cvt_pk_bf16_f32 v60, v60, v61
	v_cvt_pk_bf16_f32 v61, v62, v63
	v_cvt_pk_bf16_f32 v62, v56, v57
	v_cvt_pk_bf16_f32 v63, v58, v59
	s_and_b64 vcc, exec, s[6:7]
	s_cbranch_vccz .Lp6nt_8
	global_store_dwordx4 v[64:65], v[60:63], off
	s_branch .LBB0_641
.Lp6nt_8:
	global_store_dwordx4 v[64:65], v[60:63], off nt
	s_mov_b32 s100, 0xbfb8aa3b
	v_pk_mul_f32 v[56:57], v[52:53], s[100:101] op_sel_hi:[1,0]
	v_pk_mul_f32 v[58:59], v[54:55], s[100:101] op_sel_hi:[1,0]
	v_pk_mul_f32 v[60:61], v[48:49], s[100:101] op_sel_hi:[1,0]
	v_pk_mul_f32 v[62:63], v[50:51], s[100:101] op_sel_hi:[1,0]
	v_exp_f32_e32 v56, v56
	v_exp_f32_e32 v57, v57
	v_exp_f32_e32 v58, v58
	v_exp_f32_e32 v59, v59
	v_exp_f32_e32 v60, v60
	v_exp_f32_e32 v61, v61
	v_exp_f32_e32 v62, v62
	v_exp_f32_e32 v63, v63
	v_pk_add_f32 v[56:57], v[56:57], 1.0 op_sel_hi:[1,0]
	v_pk_add_f32 v[58:59], v[58:59], 1.0 op_sel_hi:[1,0]
	v_pk_add_f32 v[60:61], v[60:61], 1.0 op_sel_hi:[1,0]
	v_pk_add_f32 v[62:63], v[62:63], 1.0 op_sel_hi:[1,0]
	v_rcp_f32_e32 v56, v56
	v_rcp_f32_e32 v57, v57
	v_rcp_f32_e32 v58, v58
	v_rcp_f32_e32 v59, v59
	v_rcp_f32_e32 v60, v60
	v_rcp_f32_e32 v62, v62
	v_rcp_f32_e32 v63, v63
	v_rcp_f32_e32 v61, v61
	v_pk_mul_f32 v[54:55], v[54:55], v[58:59]
	v_pk_mul_f32 v[52:53], v[52:53], v[56:57]
	v_pk_mul_f32 v[50:51], v[50:51], v[62:63]
	v_pk_mul_f32 v[48:49], v[48:49], v[60:61]
.LBB0_641:
	s_mov_b32 s59, s1
	v_cvt_pk_bf16_f32 v52, v52, v53
	v_cvt_pk_bf16_f32 v53, v54, v55
	v_cvt_pk_bf16_f32 v54, v48, v49
	v_cvt_pk_bf16_f32 v55, v50, v51
	v_lshl_add_u64 v[48:49], v[64:65], 0, s[58:59]
	s_and_b64 vcc, exec, s[6:7]
	s_cbranch_vccz .Lp6nt_9
	global_store_dwordx4 v[48:49], v[52:55], off
	s_branch .LBB0_643
.Lp6nt_9:
	global_store_dwordx4 v[48:49], v[52:55], off nt
	s_mov_b32 s100, 0xbfb8aa3b
	v_pk_mul_f32 v[48:49], v[44:45], s[100:101] op_sel_hi:[1,0]
	v_pk_mul_f32 v[50:51], v[46:47], s[100:101] op_sel_hi:[1,0]
	v_pk_mul_f32 v[52:53], v[40:41], s[100:101] op_sel_hi:[1,0]
	v_pk_mul_f32 v[54:55], v[42:43], s[100:101] op_sel_hi:[1,0]
	v_exp_f32_e32 v48, v48
	v_exp_f32_e32 v49, v49
	v_exp_f32_e32 v50, v50
	v_exp_f32_e32 v51, v51
	v_exp_f32_e32 v52, v52
	v_exp_f32_e32 v53, v53
	v_exp_f32_e32 v54, v54
	v_exp_f32_e32 v55, v55
	v_pk_add_f32 v[48:49], v[48:49], 1.0 op_sel_hi:[1,0]
	v_pk_add_f32 v[50:51], v[50:51], 1.0 op_sel_hi:[1,0]
	v_pk_add_f32 v[52:53], v[52:53], 1.0 op_sel_hi:[1,0]
	v_pk_add_f32 v[54:55], v[54:55], 1.0 op_sel_hi:[1,0]
	v_rcp_f32_e32 v48, v48
	v_rcp_f32_e32 v49, v49
	v_rcp_f32_e32 v50, v50
	v_rcp_f32_e32 v51, v51
	v_rcp_f32_e32 v52, v52
	v_rcp_f32_e32 v54, v54
	v_rcp_f32_e32 v55, v55
	v_rcp_f32_e32 v53, v53
	v_pk_mul_f32 v[46:47], v[46:47], v[50:51]
	v_pk_mul_f32 v[44:45], v[44:45], v[48:49]
	v_pk_mul_f32 v[42:43], v[42:43], v[54:55]
	v_pk_mul_f32 v[40:41], v[40:41], v[52:53]
.LBB0_643:
	v_lshl_add_u64 v[48:49], v[64:65], 0, s[0:1]
	v_cvt_pk_bf16_f32 v44, v44, v45
	v_cvt_pk_bf16_f32 v45, v46, v47
	v_cvt_pk_bf16_f32 v46, v40, v41
	v_cvt_pk_bf16_f32 v47, v42, v43
	s_and_b64 vcc, exec, s[6:7]
	s_cbranch_vccz .Lp6nt_10
	global_store_dwordx4 v[48:49], v[44:47], off
	s_branch .LBB0_645
.Lp6nt_10:
	global_store_dwordx4 v[48:49], v[44:47], off nt
	s_mov_b32 s100, 0xbfb8aa3b
	v_pk_mul_f32 v[40:41], v[36:37], s[100:101] op_sel_hi:[1,0]
	v_pk_mul_f32 v[42:43], v[38:39], s[100:101] op_sel_hi:[1,0]
	v_pk_mul_f32 v[44:45], v[32:33], s[100:101] op_sel_hi:[1,0]
	v_pk_mul_f32 v[46:47], v[34:35], s[100:101] op_sel_hi:[1,0]
	v_exp_f32_e32 v40, v40
	v_exp_f32_e32 v41, v41
	v_exp_f32_e32 v42, v42
	v_exp_f32_e32 v43, v43
	v_exp_f32_e32 v44, v44
	v_exp_f32_e32 v45, v45
	v_exp_f32_e32 v46, v46
	v_exp_f32_e32 v47, v47
	v_pk_add_f32 v[40:41], v[40:41], 1.0 op_sel_hi:[1,0]
	v_pk_add_f32 v[42:43], v[42:43], 1.0 op_sel_hi:[1,0]
	v_pk_add_f32 v[44:45], v[44:45], 1.0 op_sel_hi:[1,0]
	v_pk_add_f32 v[46:47], v[46:47], 1.0 op_sel_hi:[1,0]
	v_rcp_f32_e32 v40, v40
	v_rcp_f32_e32 v41, v41
	v_rcp_f32_e32 v42, v42
	v_rcp_f32_e32 v43, v43
	v_rcp_f32_e32 v44, v44
	v_rcp_f32_e32 v46, v46
	v_rcp_f32_e32 v47, v47
	v_rcp_f32_e32 v45, v45
	v_pk_mul_f32 v[38:39], v[38:39], v[42:43]
	v_pk_mul_f32 v[36:37], v[36:37], v[40:41]
	v_pk_mul_f32 v[34:35], v[34:35], v[46:47]
	v_pk_mul_f32 v[32:33], v[32:33], v[44:45]
.LBB0_645:
	s_mov_b32 s59, s1
	v_cvt_pk_bf16_f32 v36, v36, v37
	v_cvt_pk_bf16_f32 v37, v38, v39
	v_cvt_pk_bf16_f32 v38, v32, v33
	v_cvt_pk_bf16_f32 v39, v34, v35
	v_lshl_add_u64 v[32:33], v[48:49], 0, s[58:59]
	s_and_b64 vcc, exec, s[6:7]
	s_cbranch_vccz .Lp6nt_11
	global_store_dwordx4 v[32:33], v[36:39], off
	s_branch .LBB0_647
.Lp6nt_11:
	global_store_dwordx4 v[32:33], v[36:39], off nt
	s_mov_b32 s100, 0xbfb8aa3b
	v_pk_mul_f32 v[32:33], v[28:29], s[100:101] op_sel_hi:[1,0]
	v_pk_mul_f32 v[34:35], v[30:31], s[100:101] op_sel_hi:[1,0]
	v_pk_mul_f32 v[36:37], v[24:25], s[100:101] op_sel_hi:[1,0]
	v_pk_mul_f32 v[38:39], v[26:27], s[100:101] op_sel_hi:[1,0]
	v_exp_f32_e32 v32, v32
	v_exp_f32_e32 v33, v33
	v_exp_f32_e32 v34, v34
	v_exp_f32_e32 v35, v35
	v_exp_f32_e32 v36, v36
	v_exp_f32_e32 v37, v37
	v_exp_f32_e32 v38, v38
	v_exp_f32_e32 v39, v39
	v_pk_add_f32 v[32:33], v[32:33], 1.0 op_sel_hi:[1,0]
	v_pk_add_f32 v[34:35], v[34:35], 1.0 op_sel_hi:[1,0]
	v_pk_add_f32 v[36:37], v[36:37], 1.0 op_sel_hi:[1,0]
	v_pk_add_f32 v[38:39], v[38:39], 1.0 op_sel_hi:[1,0]
	v_rcp_f32_e32 v32, v32
	v_rcp_f32_e32 v33, v33
	v_rcp_f32_e32 v34, v34
	v_rcp_f32_e32 v35, v35
	v_rcp_f32_e32 v36, v36
	v_rcp_f32_e32 v38, v38
	v_rcp_f32_e32 v39, v39
	v_rcp_f32_e32 v37, v37
	v_pk_mul_f32 v[30:31], v[30:31], v[34:35]
	v_pk_mul_f32 v[28:29], v[28:29], v[32:33]
	v_pk_mul_f32 v[26:27], v[26:27], v[38:39]
	v_pk_mul_f32 v[24:25], v[24:25], v[36:37]
.LBB0_647:
	v_lshl_add_u64 v[32:33], v[48:49], 0, s[0:1]
	v_cvt_pk_bf16_f32 v28, v28, v29
	v_cvt_pk_bf16_f32 v29, v30, v31
	v_cvt_pk_bf16_f32 v30, v24, v25
	v_cvt_pk_bf16_f32 v31, v26, v27
	s_and_b64 vcc, exec, s[6:7]
	s_cbranch_vccz .Lp6nt_12
	global_store_dwordx4 v[32:33], v[28:31], off
	s_branch .LBB0_649
.Lp6nt_12:
	global_store_dwordx4 v[32:33], v[28:31], off nt
	s_mov_b32 s100, 0xbfb8aa3b
	v_pk_mul_f32 v[24:25], v[20:21], s[100:101] op_sel_hi:[1,0]
	v_pk_mul_f32 v[26:27], v[22:23], s[100:101] op_sel_hi:[1,0]
	v_pk_mul_f32 v[28:29], v[16:17], s[100:101] op_sel_hi:[1,0]
	v_pk_mul_f32 v[30:31], v[18:19], s[100:101] op_sel_hi:[1,0]
	v_exp_f32_e32 v24, v24
	v_exp_f32_e32 v25, v25
	v_exp_f32_e32 v26, v26
	v_exp_f32_e32 v27, v27
	v_exp_f32_e32 v28, v28
	v_exp_f32_e32 v29, v29
	v_exp_f32_e32 v30, v30
	v_exp_f32_e32 v31, v31
	v_pk_add_f32 v[24:25], v[24:25], 1.0 op_sel_hi:[1,0]
	v_pk_add_f32 v[26:27], v[26:27], 1.0 op_sel_hi:[1,0]
	v_pk_add_f32 v[28:29], v[28:29], 1.0 op_sel_hi:[1,0]
	v_pk_add_f32 v[30:31], v[30:31], 1.0 op_sel_hi:[1,0]
	v_rcp_f32_e32 v24, v24
	v_rcp_f32_e32 v25, v25
	v_rcp_f32_e32 v26, v26
	v_rcp_f32_e32 v27, v27
	v_rcp_f32_e32 v28, v28
	v_rcp_f32_e32 v30, v30
	v_rcp_f32_e32 v31, v31
	v_rcp_f32_e32 v29, v29
	v_pk_mul_f32 v[22:23], v[22:23], v[26:27]
	v_pk_mul_f32 v[20:21], v[20:21], v[24:25]
	v_pk_mul_f32 v[18:19], v[18:19], v[30:31]
	v_pk_mul_f32 v[16:17], v[16:17], v[28:29]
.LBB0_649:
	s_mov_b32 s59, s1
	v_cvt_pk_bf16_f32 v20, v20, v21
	v_cvt_pk_bf16_f32 v21, v22, v23
	v_cvt_pk_bf16_f32 v22, v16, v17
	v_cvt_pk_bf16_f32 v23, v18, v19
	v_lshl_add_u64 v[16:17], v[32:33], 0, s[58:59]
	s_and_b64 vcc, exec, s[6:7]
	s_cbranch_vccz .Lp6nt_13
	global_store_dwordx4 v[16:17], v[20:23], off
	s_branch .LBB0_651
.Lp6nt_13:
	global_store_dwordx4 v[16:17], v[20:23], off nt
	s_mov_b32 s100, 0xbfb8aa3b
	v_pk_mul_f32 v[16:17], v[12:13], s[100:101] op_sel_hi:[1,0]
	v_pk_mul_f32 v[18:19], v[14:15], s[100:101] op_sel_hi:[1,0]
	v_pk_mul_f32 v[20:21], v[8:9], s[100:101] op_sel_hi:[1,0]
	v_pk_mul_f32 v[22:23], v[10:11], s[100:101] op_sel_hi:[1,0]
	v_exp_f32_e32 v16, v16
	v_exp_f32_e32 v17, v17
	v_exp_f32_e32 v18, v18
	v_exp_f32_e32 v19, v19
	v_exp_f32_e32 v20, v20
	v_exp_f32_e32 v21, v21
	v_exp_f32_e32 v22, v22
	v_exp_f32_e32 v23, v23
	v_pk_add_f32 v[16:17], v[16:17], 1.0 op_sel_hi:[1,0]
	v_pk_add_f32 v[18:19], v[18:19], 1.0 op_sel_hi:[1,0]
	v_pk_add_f32 v[20:21], v[20:21], 1.0 op_sel_hi:[1,0]
	v_pk_add_f32 v[22:23], v[22:23], 1.0 op_sel_hi:[1,0]
	v_rcp_f32_e32 v16, v16
	v_rcp_f32_e32 v17, v17
	v_rcp_f32_e32 v18, v18
	v_rcp_f32_e32 v19, v19
	v_rcp_f32_e32 v20, v20
	v_rcp_f32_e32 v22, v22
	v_rcp_f32_e32 v23, v23
	v_rcp_f32_e32 v21, v21
	v_pk_mul_f32 v[14:15], v[14:15], v[18:19]
	v_pk_mul_f32 v[12:13], v[12:13], v[16:17]
	v_pk_mul_f32 v[10:11], v[10:11], v[22:23]
	v_pk_mul_f32 v[8:9], v[8:9], v[20:21]
.LBB0_651:
	v_lshl_add_u64 v[16:17], v[32:33], 0, s[0:1]
	v_cvt_pk_bf16_f32 v12, v12, v13
	v_cvt_pk_bf16_f32 v13, v14, v15
	v_cvt_pk_bf16_f32 v14, v8, v9
	v_cvt_pk_bf16_f32 v15, v10, v11
	s_and_b64 vcc, exec, s[6:7]
	s_cbranch_vccz .Lp6nt_14
	global_store_dwordx4 v[16:17], v[12:15], off
	s_branch .LBB0_608
.Lp6nt_14:
	global_store_dwordx4 v[16:17], v[12:15], off nt
	s_mov_b32 s100, 0xbfb8aa3b
	v_pk_mul_f32 v[8:9], v[4:5], s[100:101] op_sel_hi:[1,0]
	v_pk_mul_f32 v[10:11], v[6:7], s[100:101] op_sel_hi:[1,0]
	v_pk_mul_f32 v[12:13], v[0:1], s[100:101] op_sel_hi:[1,0]
	v_pk_mul_f32 v[14:15], v[2:3], s[100:101] op_sel_hi:[1,0]
	v_exp_f32_e32 v8, v8
	v_exp_f32_e32 v9, v9
	v_exp_f32_e32 v10, v10
	v_exp_f32_e32 v11, v11
	v_exp_f32_e32 v12, v12
	v_exp_f32_e32 v13, v13
	v_exp_f32_e32 v14, v14
	v_exp_f32_e32 v15, v15
	v_pk_add_f32 v[8:9], v[8:9], 1.0 op_sel_hi:[1,0]
	v_pk_add_f32 v[10:11], v[10:11], 1.0 op_sel_hi:[1,0]
	v_pk_add_f32 v[12:13], v[12:13], 1.0 op_sel_hi:[1,0]
	v_pk_add_f32 v[14:15], v[14:15], 1.0 op_sel_hi:[1,0]
	v_rcp_f32_e32 v8, v8
	v_rcp_f32_e32 v9, v9
	v_rcp_f32_e32 v10, v10
	v_rcp_f32_e32 v11, v11
	v_rcp_f32_e32 v12, v12
	v_rcp_f32_e32 v14, v14
	v_rcp_f32_e32 v15, v15
	v_rcp_f32_e32 v13, v13
	v_pk_mul_f32 v[6:7], v[6:7], v[10:11]
	v_pk_mul_f32 v[4:5], v[4:5], v[8:9]
	v_pk_mul_f32 v[2:3], v[2:3], v[14:15]
	v_pk_mul_f32 v[0:1], v[0:1], v[12:13]
	s_branch .LBB0_608
